# stick-breaking loop: the eight per-step cross-half group-sum exchanges done with v_permlane32_swap + v_cndmask instead of ds_bpermute + LDS wait
# baseline (speedup 1.0000x reference)
; DI float fexp2(float x) { return __builtin_amdgcn_exp2f(x); }
; template <int TYPE>
; DI void attn_item(KargPtr p, int b, int h, int qb, unsigned char* smem) {
;     ...
;                 float run = carry;
; #pragma unroll
;                 for (int g = 3; g >= 0; --g) {
;                     const float G = (lk1[4 * g] + lk1[4 * g + 1]) + (lk1[4 * g + 2] + lk1[4 * g + 3]);
;                     const float Gp = __shfl_xor(G, 32);
;                     const float base = run + (hh == 0 ? Gp : 0.f);
;                     const float e3 = base, e2 = e3 + lk1[4 * g + 3], e1 = e2 + lk1[4 * g + 2], e0 = e1 + lk1[4 * g + 1];
;                     s1[4 * g + 3] = fexp2(s1[4 * g + 3] + e3); s1[4 * g + 2] = fexp2(s1[4 * g + 2] + e2);
;                     s1[4 * g + 1] = fexp2(s1[4 * g + 1] + e1); s1[4 * g] = fexp2(s1[4 * g] + e0);
;                     run += G + Gp;
;                 }
; #pragma unroll
;                 for (int g = 3; g >= 0; --g) {
;                     const float G = (lk0[4 * g] + lk0[4 * g + 1]) + (lk0[4 * g + 2] + lk0[4 * g + 3]);
;                     const float Gp = __shfl_xor(G, 32);
;                     const float base = run + (hh == 0 ? Gp : 0.f);
;                     const float e3 = base, e2 = e3 + lk0[4 * g + 3], e1 = e2 + lk0[4 * g + 2], e0 = e1 + lk0[4 * g + 1];
;                     s0[4 * g + 3] = fexp2(s0[4 * g + 3] + e3); s0[4 * g + 2] = fexp2(s0[4 * g + 2] + e2);
;                     s0[4 * g + 1] = fexp2(s0[4 * g + 1] + e1); s0[4 * g] = fexp2(s0[4 * g] + e0);
;                     run += G + Gp;
;                 }
;                 carry = run;
.LBB0_575:
	s_or_b64 exec, exec, s[90:91]
	v_and_b32_e32 v67, 64, v205
	v_xor_b32_e32 v66, 32, v205
	v_add_u32_e32 v67, 64, v67
	v_cmp_lt_i32_e32 vcc, v66, v67
	v_add_f32_e32 v70, v60, v65
	v_mov_b32_e32 v67, v62
	v_cndmask_b32_e32 v66, v205, v66, vcc
	v_lshlrev_b32_e32 v68, 2, v66
	v_add_f32_e32 v66, v64, v63
	v_mov_b32_e32 v71, v59
	v_pk_add_f32 v[66:67], v[66:67], v[70:71]
	v_mov_b32_e32 v72, v66
	v_mov_b32_e32 v245, v66
	s_nop 1
	v_permlane32_swap_b32_e32 v72, v245
	v_cndmask_b32_e64 v72, v72, v245, s[4:5]
	v_add_f32_e32 v73, v58, v61
	v_mov_b32_e32 v74, v52
	v_mov_b32_e32 v75, v53
	s_waitcnt lgkmcnt(0)
	v_pk_add_f32 v[66:67], v[66:67], v[72:73]
	v_mov_b32_e32 v165, v67
	v_mov_b32_e32 v244, v67
	s_nop 1
	v_permlane32_swap_b32_e32 v165, v244
	v_cndmask_b32_e64 v165, v165, v244, s[4:5]
	v_cndmask_b32_e64 v62, 0, v72, s[4:5]
	v_add_f32_e32 v62, v164, v62
	v_add_f32_e32 v64, v65, v62
	v_add_f32_e32 v65, v60, v64
	v_add_f32_e32 v69, v63, v65
	v_add_f32_e32 v63, v195, v65
	s_waitcnt lgkmcnt(0)
	v_cndmask_b32_e64 v65, 0, v165, s[4:5]
	v_pk_add_f32 v[70:71], v[164:165], v[66:67]
	v_mov_b32_e32 v72, v56
	v_add_f32_e32 v65, v70, v65
	v_add_f32_e32 v66, v61, v65
	v_add_f32_e32 v58, v58, v66
	v_add_f32_e32 v59, v59, v58
	v_add_f32_e32 v58, v191, v58
	v_add_f32_e32 v61, v193, v65
	v_add_f32_e32 v65, v192, v66
	v_exp_f32_e32 v66, v58
	v_add_f32_e32 v58, v190, v59
	v_exp_f32_e32 v67, v58
	v_pk_add_f32 v[58:59], v[70:71], v[70:71] op_sel:[0,1] op_sel_hi:[1,0]
	v_mov_b32_e32 v70, v55
	v_mov_b32_e32 v71, v54
	v_mov_b32_e32 v73, v57
	v_pk_add_f32 v[70:71], v[70:71], v[72:73]
	v_add_f32_e32 v60, v197, v62
	v_add_f32_e32 v56, v70, v71
	v_mov_b32_e32 v59, v56
	v_mov_b32_e32 v243, v56
	s_nop 1
	v_permlane32_swap_b32_e32 v59, v243
	v_cndmask_b32_e64 v59, v59, v243, s[4:5]
	v_add_f32_e32 v62, v196, v64
	v_add_f32_e32 v64, v194, v69
	v_exp_f32_e32 v60, v60
	v_exp_f32_e32 v62, v62
	s_waitcnt lgkmcnt(0)
	v_cndmask_b32_e64 v69, 0, v59, s[4:5]
	v_add_f32_e32 v69, v58, v69
	v_add_f32_e32 v57, v57, v69
	v_add_f32_e32 v54, v54, v57
	v_add_f32_e32 v55, v55, v54
	v_add_f32_e32 v54, v187, v54
	v_exp_f32_e32 v71, v54
	v_add_f32_e32 v54, v186, v55
	v_exp_f32_e32 v72, v54
	v_mov_b32_e32 v54, v51
	v_mov_b32_e32 v55, v50
	v_pk_add_f32 v[54:55], v[54:55], v[74:75]
	v_add_f32_e32 v57, v188, v57
	v_pk_add_f32 v[54:55], v[54:55], v[54:55] op_sel:[0,1] op_sel_hi:[1,0]
	v_mov_b32_e32 v52, v54
	v_mov_b32_e32 v242, v54
	s_nop 1
	v_permlane32_swap_b32_e32 v52, v242
	v_cndmask_b32_e64 v52, v52, v242, s[4:5]
	v_exp_f32_e32 v70, v57
	v_add_f32_e32 v56, v56, v59
	v_mov_b32_e32 v59, v14
	v_mov_b32_e32 v57, v49
	s_waitcnt lgkmcnt(0)
	v_cndmask_b32_e64 v55, 0, v52, s[4:5]
	v_pk_add_f32 v[56:57], v[58:59], v[56:57]
	v_add_f32_e32 v69, v189, v69
	v_add_f32_e32 v55, v56, v55
	v_add_f32_e32 v53, v53, v55
	v_add_f32_e32 v58, v50, v53
	v_add_f32_e32 v59, v51, v58
	v_add_f32_e32 v51, v184, v53
	v_add_f32_e32 v53, v181, v58
	v_exp_f32_e32 v58, v53
	v_add_f32_e32 v53, v180, v59
	v_add_f32_e32 v50, v185, v55
	v_exp_f32_e32 v59, v53
	v_mov_b32_e32 v55, v48
	v_mov_b32_e32 v53, v15
	v_pk_add_f32 v[52:53], v[54:55], v[52:53]
	v_exp_f32_e32 v69, v69
	v_pk_add_f32 v[54:55], v[52:53], v[56:57]
	v_mov_b32_e32 v56, v55
	v_mov_b32_e32 v241, v55
	s_nop 1
	v_permlane32_swap_b32_e32 v56, v241
	v_cndmask_b32_e64 v56, v56, v241, s[4:5]
	v_mov_b32_e32 v57, v11
	v_exp_f32_e32 v50, v50
	v_exp_f32_e32 v51, v51
	v_exp_f32_e32 v63, v63
	s_waitcnt lgkmcnt(0)
; template <int TYPE>
; DI void attn_item(KargPtr p, int b, int h, int qb, unsigned char* smem) {
;     ...
;                 float run = carry;
; #pragma unroll
;                 for (int g = 3; g >= 0; --g) {
;                     const float G = (lk1[4 * g] + lk1[4 * g + 1]) + (lk1[4 * g + 2] + lk1[4 * g + 3]);
;                     const float Gp = __shfl_xor(G, 32);
;                     const float base = run + (hh == 0 ? Gp : 0.f);
;                     const float e3 = base, e2 = e3 + lk1[4 * g + 3], e1 = e2 + lk1[4 * g + 2], e0 = e1 + lk1[4 * g + 1];
;                     s1[4 * g + 3] = fexp2(s1[4 * g + 3] + e3); s1[4 * g + 2] = fexp2(s1[4 * g + 2] + e2);
;                     s1[4 * g + 1] = fexp2(s1[4 * g + 1] + e1); s1[4 * g] = fexp2(s1[4 * g] + e0);
;                     run += G + Gp;
;                 }
; #pragma unroll
;                 for (int g = 3; g >= 0; --g) {
;                     const float G = (lk0[4 * g] + lk0[4 * g + 1]) + (lk0[4 * g + 2] + lk0[4 * g + 3]);
;                     const float Gp = __shfl_xor(G, 32);
;                     const float base = run + (hh == 0 ? Gp : 0.f);
;                     const float e3 = base, e2 = e3 + lk0[4 * g + 3], e1 = e2 + lk0[4 * g + 2], e0 = e1 + lk0[4 * g + 1];
;                     s0[4 * g + 3] = fexp2(s0[4 * g + 3] + e3); s0[4 * g + 2] = fexp2(s0[4 * g + 2] + e2);
;                     s0[4 * g + 1] = fexp2(s0[4 * g + 1] + e1); s0[4 * g] = fexp2(s0[4 * g] + e0);
;                     run += G + Gp;
;                 }
;                 carry = run;
;             }
; #pragma unroll
;             for (int s2 = 0; s2 < 2; ++s2) {
;                 unsigned pk0[4], pk1[4];
; #pragma unroll
;                 for (int j = 0; j < 4; ++j) { pk0[j] = pack_bf16(s0[8 * s2 + 2 * j], s0[8 * s2 + 2 * j + 1]); pk1[j] = pack_bf16(s1[8 * s2 + 2 * j], s1[8 * s2 + 2 * j + 1]); }
;                 const uint4 u0 = make_uint4(pk0[0], pk0[1], pk0[2], pk0[3]), u1 = make_uint4(pk1[0], pk1[1], pk1[2], pk1[3]);
;                 const bf16x8 pf0 = __builtin_bit_cast(bf16x8, u0), pf1 = __builtin_bit_cast(bf16x8, u1);
;                 const bf16x8 v00 = *(const bf16x8*)(vb + r * VROWB + (16 * s2 + 8 * hh) * 2);
;                 const bf16x8 v01 = *(const bf16x8*)(vb + (32 + r) * VROWB + (16 * s2 + 8 * hh) * 2);
;                 const bf16x8 v10 = *(const bf16x8*)(vb + r * VROWB + (32 + 16 * s2 + 8 * hh) * 2);
	v_cndmask_b32_e64 v48, 0, v56, s[4:5]
	v_add_f32_e32 v48, v54, v48
	v_add_f32_e32 v49, v49, v48
	v_add_f32_e32 v14, v14, v49
	v_add_f32_e32 v15, v15, v14
	v_add_f32_e32 v14, v179, v14
	v_exp_f32_e32 v52, v14
	v_add_f32_e32 v14, v178, v15
	v_exp_f32_e32 v53, v14
	v_add_f32_e32 v14, v55, v56
	v_add_f32_e32 v14, v54, v14
	v_mov_b32_e32 v54, v13
	v_mov_b32_e32 v55, v10
	v_mov_b32_e32 v56, v12
	v_pk_add_f32 v[54:55], v[54:55], v[56:57]
	v_add_f32_e32 v48, v183, v48
	v_add_f32_e32 v12, v54, v55
	v_mov_b32_e32 v15, v12
	v_mov_b32_e32 v240, v12
	s_nop 1
	v_permlane32_swap_b32_e32 v15, v240
	v_cndmask_b32_e64 v15, v15, v240, s[4:5]
	v_mov_b32_e32 v55, v7
	v_add_f32_e32 v49, v182, v49
	v_exp_f32_e32 v48, v48
	v_exp_f32_e32 v49, v49
	s_waitcnt lgkmcnt(0)
	v_cndmask_b32_e64 v54, 0, v15, s[4:5]
	v_add_f32_e32 v54, v14, v54
	v_add_f32_e32 v11, v11, v54
	v_add_f32_e32 v10, v10, v11
	v_add_f32_e32 v13, v13, v10
	v_add_f32_e32 v10, v175, v10
	v_add_f32_e32 v54, v177, v54
	v_exp_f32_e32 v138, v10
	v_add_f32_e32 v10, v174, v13
	v_exp_f32_e32 v80, v54
	v_exp_f32_e32 v139, v10
	v_add_f32_e32 v10, v12, v15
	v_mov_b32_e32 v12, v9
	v_mov_b32_e32 v13, v6
	v_mov_b32_e32 v54, v8
	v_pk_add_f32 v[12:13], v[12:13], v[54:55]
	v_add_f32_e32 v11, v176, v11
	v_pk_add_f32 v[12:13], v[12:13], v[12:13] op_sel:[0,1] op_sel_hi:[1,0]
	v_mov_b32_e32 v8, v12
	v_mov_b32_e32 v239, v12
	s_nop 1
	v_permlane32_swap_b32_e32 v8, v239
	v_cndmask_b32_e64 v8, v8, v239, s[4:5]
	v_exp_f32_e32 v81, v11
	v_mov_b32_e32 v15, v4
	v_mov_b32_e32 v11, v5
	v_pk_add_f32 v[10:11], v[14:15], v[10:11]
	s_waitcnt lgkmcnt(0)
	v_cndmask_b32_e64 v13, 0, v8, s[4:5]
	v_add_f32_e32 v13, v10, v13
	v_add_f32_e32 v7, v7, v13
	v_add_f32_e32 v6, v6, v7
	v_add_f32_e32 v9, v9, v6
	v_add_f32_e32 v13, v173, v13
	v_add_f32_e32 v6, v171, v6
	v_exp_f32_e32 v14, v13
	v_add_f32_e32 v7, v172, v7
	v_exp_f32_e32 v54, v6
	v_add_f32_e32 v6, v170, v9
	v_mov_b32_e32 v13, v0
	v_mov_b32_e32 v9, v1
	v_exp_f32_e32 v15, v7
	v_exp_f32_e32 v55, v6
	v_pk_add_f32 v[6:7], v[12:13], v[8:9]
	v_exp_f32_e32 v64, v64
	v_pk_add_f32 v[6:7], v[6:7], v[10:11]
	v_mov_b32_e32 v0, v7
	v_mov_b32_e32 v238, v7
	s_nop 1
	v_permlane32_swap_b32_e32 v0, v238
	v_cndmask_b32_e64 v0, v0, v238, s[4:5]
	v_cvt_pk_bf16_f32 v10, v72, v71
	v_cvt_pk_bf16_f32 v11, v70, v69
	v_exp_f32_e32 v61, v61
	v_exp_f32_e32 v65, v65
	s_waitcnt lgkmcnt(0)
	v_cndmask_b32_e64 v8, 0, v0, s[4:5]
	v_add_f32_e32 v8, v6, v8
	v_add_f32_e32 v5, v5, v8
	v_add_f32_e32 v4, v4, v5
	v_add_f32_e32 v1, v1, v4
	v_add_f32_e32 v8, v169, v8
	v_add_f32_e32 v5, v168, v5
	v_add_f32_e32 v4, v167, v4
	v_add_f32_e32 v1, v166, v1
	v_exp_f32_e32 v9, v8
	v_exp_f32_e32 v5, v5
	v_exp_f32_e32 v4, v4
	v_exp_f32_e32 v1, v1
	v_add_f32_e32 v0, v7, v0
	v_add_f32_e32 v164, v6, v0
	v_cvt_pk_bf16_f32 v6, v55, v54
	v_cvt_pk_bf16_f32 v7, v15, v14
	ds_read_b128 v[12:15], v224 offset:13824
	ds_read_b128 v[54:57], v224 offset:9280
	ds_read_b128 v[68:71], v224 offset:13888
	ds_read_b128 v[72:75], v224 offset:9216
	ds_read_b128 v[76:79], v224 offset:9248
	v_cvt_pk_bf16_f32 v4, v1, v4
	v_cvt_pk_bf16_f32 v5, v5, v9
	v_cvt_pk_bf16_f32 v8, v59, v58
	v_cvt_pk_bf16_f32 v9, v51, v50
	s_waitcnt lgkmcnt(1)
	v_mfma_f32_32x32x16_bf16 v[32:47], v[72:75], v[4:7], v[32:47]
	v_mfma_f32_32x32x16_bf16 v[16:31], v[12:15], v[4:7], v[16:31]
	v_cvt_pk_bf16_f32 v6, v53, v52
	v_cvt_pk_bf16_f32 v7, v49, v48
	v_cvt_pk_bf16_f32 v4, v139, v138
	v_cvt_pk_bf16_f32 v5, v81, v80
	v_mfma_f32_32x32x16_bf16 v[32:47], v[54:57], v[8:11], v[32:47]
	ds_read_b128 v[12:15], v224 offset:13856
	ds_read_b128 v[48:51], v224 offset:9312
	ds_read_b128 v[52:55], v224 offset:13920
	v_mfma_f32_32x32x16_bf16 v[16:31], v[68:71], v[8:11], v[16:31]
	v_cvt_pk_bf16_f32 v8, v67, v66
	v_cvt_pk_bf16_f32 v9, v65, v61
	v_cvt_pk_bf16_f32 v10, v64, v63
	v_cvt_pk_bf16_f32 v11, v62, v60
	s_waitcnt lgkmcnt(3)
	v_mfma_f32_32x32x16_bf16 v[32:47], v[76:79], v[4:7], v[32:47]
	s_waitcnt lgkmcnt(2)
	v_mfma_f32_32x32x16_bf16 v[16:31], v[12:15], v[4:7], v[16:31]
	s_waitcnt lgkmcnt(1)
	v_mfma_f32_32x32x16_bf16 v[32:47], v[48:51], v[8:11], v[32:47]
	s_waitcnt lgkmcnt(0)
	v_mfma_f32_32x32x16_bf16 v[16:31], v[52:55], v[8:11], v[16:31]

; DI float fexp2(float x) { return __builtin_amdgcn_exp2f(x); }
; template <int TYPE>
; DI void attn_item(KargPtr p, int b, int h, int qb, unsigned char* smem) {
;     ...
;                 float run = carry;
; #pragma unroll
;                 for (int g = 3; g >= 0; --g) {
;                     const float G = (lk1[4 * g] + lk1[4 * g + 1]) + (lk1[4 * g + 2] + lk1[4 * g + 3]);
;                     const float Gp = __shfl_xor(G, 32);
;                     const float base = run + (hh == 0 ? Gp : 0.f);
;                     const float e3 = base, e2 = e3 + lk1[4 * g + 3], e1 = e2 + lk1[4 * g + 2], e0 = e1 + lk1[4 * g + 1];
;                     s1[4 * g + 3] = fexp2(s1[4 * g + 3] + e3); s1[4 * g + 2] = fexp2(s1[4 * g + 2] + e2);
;                     s1[4 * g + 1] = fexp2(s1[4 * g + 1] + e1); s1[4 * g] = fexp2(s1[4 * g] + e0);
;                     run += G + Gp;
;                 }
; #pragma unroll
;                 for (int g = 3; g >= 0; --g) {
;                     const float G = (lk0[4 * g] + lk0[4 * g + 1]) + (lk0[4 * g + 2] + lk0[4 * g + 3]);
;                     const float Gp = __shfl_xor(G, 32);
;                     const float base = run + (hh == 0 ? Gp : 0.f);
;                     const float e3 = base, e2 = e3 + lk0[4 * g + 3], e1 = e2 + lk0[4 * g + 2], e0 = e1 + lk0[4 * g + 1];
;                     s0[4 * g + 3] = fexp2(s0[4 * g + 3] + e3); s0[4 * g + 2] = fexp2(s0[4 * g + 2] + e2);
;                     s0[4 * g + 1] = fexp2(s0[4 * g + 1] + e1); s0[4 * g] = fexp2(s0[4 * g] + e0);
;                     run += G + Gp;
;                 }
;                 carry = run;
.LBB0_582:
	s_or_b64 exec, exec, s[90:91]
	v_and_b32_e32 v66, 64, v205
	v_xor_b32_e32 v64, 32, v205
	v_add_u32_e32 v66, 64, v66
	v_cmp_lt_i32_e32 vcc, v64, v66
	v_add_f32_e32 v66, v62, v63
	v_add_f32_e32 v70, v58, v65
	v_cndmask_b32_e32 v64, v205, v64, vcc
	v_mov_b32_e32 v67, v60
	v_mov_b32_e32 v71, v59
	v_lshlrev_b32_e32 v68, 2, v64
	v_pk_add_f32 v[66:67], v[66:67], v[70:71]
	v_mov_b32_e32 v72, v66
	v_mov_b32_e32 v237, v66
	s_nop 1
	v_permlane32_swap_b32_e32 v72, v237
	v_cndmask_b32_e64 v72, v72, v237, s[4:5]
	v_add_f32_e32 v73, v56, v61
	s_waitcnt lgkmcnt(0)
	v_cndmask_b32_e64 v60, 0, v72, s[4:5]
	v_pk_add_f32 v[66:67], v[66:67], v[72:73]
	v_add_f32_e32 v60, v164, v60
	v_mov_b32_e32 v165, v67
	v_mov_b32_e32 v236, v67
	s_nop 1
	v_permlane32_swap_b32_e32 v165, v236
	v_cndmask_b32_e64 v165, v165, v236, s[4:5]
	v_add_f32_e32 v62, v65, v60
	v_add_f32_e32 v58, v58, v62
	v_add_f32_e32 v64, v63, v58
	v_add_f32_e32 v58, v195, v58
	v_exp_f32_e32 v63, v58
	v_add_f32_e32 v58, v194, v64
	v_exp_f32_e32 v64, v58
	s_waitcnt lgkmcnt(0)
	v_cndmask_b32_e64 v58, 0, v165, s[4:5]
	v_pk_add_f32 v[70:71], v[164:165], v[66:67]
	v_mov_b32_e32 v72, v54
	v_add_f32_e32 v58, v70, v58
	v_add_f32_e32 v65, v61, v58
	v_add_f32_e32 v56, v56, v65
	v_add_f32_e32 v58, v193, v58
	v_add_f32_e32 v59, v59, v56
	v_exp_f32_e32 v61, v58
	v_add_f32_e32 v58, v192, v65
	v_add_f32_e32 v56, v191, v56
	v_exp_f32_e32 v65, v58
	v_exp_f32_e32 v66, v56
	v_add_f32_e32 v56, v190, v59
	v_pk_add_f32 v[58:59], v[70:71], v[70:71] op_sel:[0,1] op_sel_hi:[1,0]
	v_mov_b32_e32 v70, v55
	v_mov_b32_e32 v71, v52
	v_mov_b32_e32 v73, v57
	v_pk_add_f32 v[70:71], v[70:71], v[72:73]
	v_exp_f32_e32 v67, v56
	v_add_f32_e32 v54, v70, v71
	v_mov_b32_e32 v56, v54
	v_mov_b32_e32 v235, v54
	s_nop 1
	v_permlane32_swap_b32_e32 v56, v235
	v_cndmask_b32_e64 v56, v56, v235, s[4:5]
	v_mov_b32_e32 v72, v50
	v_mov_b32_e32 v73, v53
	v_add_f32_e32 v60, v197, v60
	v_add_f32_e32 v62, v196, v62
	s_waitcnt lgkmcnt(0)
	v_cndmask_b32_e64 v59, 0, v56, s[4:5]
	v_add_f32_e32 v59, v58, v59
	v_add_f32_e32 v57, v57, v59
	v_add_f32_e32 v70, v52, v57
	v_add_f32_e32 v55, v55, v70
	v_add_f32_e32 v55, v186, v55
	v_exp_f32_e32 v71, v55
	v_add_f32_e32 v56, v54, v56
	v_mov_b32_e32 v54, v51
	v_mov_b32_e32 v55, v48
	v_pk_add_f32 v[54:55], v[54:55], v[72:73]
	v_add_f32_e32 v57, v188, v57
	v_pk_add_f32 v[54:55], v[54:55], v[54:55] op_sel:[0,1] op_sel_hi:[1,0]
	v_mov_b32_e32 v50, v54
	v_mov_b32_e32 v234, v54
	s_nop 1
	v_permlane32_swap_b32_e32 v50, v234
	v_cndmask_b32_e64 v50, v50, v234, s[4:5]
	v_exp_f32_e32 v69, v57
	v_add_f32_e32 v57, v187, v70
	v_add_f32_e32 v52, v189, v59
	v_exp_f32_e32 v70, v57
	v_mov_b32_e32 v59, v14
	v_mov_b32_e32 v57, v49
	s_waitcnt lgkmcnt(0)
	v_cndmask_b32_e64 v55, 0, v50, s[4:5]
	v_pk_add_f32 v[56:57], v[58:59], v[56:57]
	v_exp_f32_e32 v52, v52
	v_add_f32_e32 v55, v56, v55
	v_add_f32_e32 v53, v53, v55
	v_add_f32_e32 v58, v48, v53
	v_add_f32_e32 v51, v51, v58
	v_add_f32_e32 v48, v185, v55
	v_add_f32_e32 v55, v181, v58
	v_add_f32_e32 v51, v180, v51
	v_exp_f32_e32 v58, v55
	v_exp_f32_e32 v59, v51
	v_mov_b32_e32 v55, v12
	v_mov_b32_e32 v51, v15
	v_pk_add_f32 v[50:51], v[54:55], v[50:51]
	v_add_f32_e32 v53, v184, v53
	v_pk_add_f32 v[54:55], v[50:51], v[56:57]
	v_mov_b32_e32 v12, v55
	v_mov_b32_e32 v233, v55
	s_nop 1
	v_permlane32_swap_b32_e32 v12, v233
	v_cndmask_b32_e64 v12, v12, v233, s[4:5]
	v_mov_b32_e32 v57, v11
	v_exp_f32_e32 v48, v48
	v_exp_f32_e32 v53, v53
	v_exp_f32_e32 v60, v60
	s_waitcnt lgkmcnt(0)
; template <int TYPE>
; DI void attn_item(KargPtr p, int b, int h, int qb, unsigned char* smem) {
;     ...
;                 float run = carry;
; #pragma unroll
;                 for (int g = 3; g >= 0; --g) {
;                     const float G = (lk1[4 * g] + lk1[4 * g + 1]) + (lk1[4 * g + 2] + lk1[4 * g + 3]);
;                     const float Gp = __shfl_xor(G, 32);
;                     const float base = run + (hh == 0 ? Gp : 0.f);
;                     const float e3 = base, e2 = e3 + lk1[4 * g + 3], e1 = e2 + lk1[4 * g + 2], e0 = e1 + lk1[4 * g + 1];
;                     s1[4 * g + 3] = fexp2(s1[4 * g + 3] + e3); s1[4 * g + 2] = fexp2(s1[4 * g + 2] + e2);
;                     s1[4 * g + 1] = fexp2(s1[4 * g + 1] + e1); s1[4 * g] = fexp2(s1[4 * g] + e0);
;                     run += G + Gp;
;                 }
; #pragma unroll
;                 for (int g = 3; g >= 0; --g) {
;                     const float G = (lk0[4 * g] + lk0[4 * g + 1]) + (lk0[4 * g + 2] + lk0[4 * g + 3]);
;                     const float Gp = __shfl_xor(G, 32);
;                     const float base = run + (hh == 0 ? Gp : 0.f);
;                     const float e3 = base, e2 = e3 + lk0[4 * g + 3], e1 = e2 + lk0[4 * g + 2], e0 = e1 + lk0[4 * g + 1];
;                     s0[4 * g + 3] = fexp2(s0[4 * g + 3] + e3); s0[4 * g + 2] = fexp2(s0[4 * g + 2] + e2);
;                     s0[4 * g + 1] = fexp2(s0[4 * g + 1] + e1); s0[4 * g] = fexp2(s0[4 * g] + e0);
;                     run += G + Gp;
;                 }
;                 carry = run;
;             }
; #pragma unroll
;             for (int s2 = 0; s2 < 2; ++s2) {
;                 unsigned pk0[4], pk1[4];
; #pragma unroll
;                 for (int j = 0; j < 4; ++j) { pk0[j] = pack_bf16(s0[8 * s2 + 2 * j], s0[8 * s2 + 2 * j + 1]); pk1[j] = pack_bf16(s1[8 * s2 + 2 * j], s1[8 * s2 + 2 * j + 1]); }
;                 const uint4 u0 = make_uint4(pk0[0], pk0[1], pk0[2], pk0[3]), u1 = make_uint4(pk1[0], pk1[1], pk1[2], pk1[3]);
;                 const bf16x8 pf0 = __builtin_bit_cast(bf16x8, u0), pf1 = __builtin_bit_cast(bf16x8, u1);
;                 const bf16x8 v00 = *(const bf16x8*)(vb + r * VROWB + (16 * s2 + 8 * hh) * 2);
;                 const bf16x8 v01 = *(const bf16x8*)(vb + (32 + r) * VROWB + (16 * s2 + 8 * hh) * 2);
;                 const bf16x8 v10 = *(const bf16x8*)(vb + r * VROWB + (32 + 16 * s2 + 8 * hh) * 2);
	v_cndmask_b32_e64 v50, 0, v12, s[4:5]
	v_add_f32_e32 v50, v54, v50
	v_add_f32_e32 v49, v49, v50
	v_add_f32_e32 v51, v14, v49
	v_add_f32_e32 v56, v15, v51
	v_add_f32_e32 v12, v55, v12
	v_add_f32_e32 v14, v183, v50
	v_add_f32_e32 v50, v178, v56
	v_add_f32_e32 v12, v54, v12
	v_mov_b32_e32 v54, v13
	v_mov_b32_e32 v55, v10
	v_mov_b32_e32 v56, v8
	v_pk_add_f32 v[54:55], v[54:55], v[56:57]
	v_add_f32_e32 v15, v182, v49
	v_add_f32_e32 v8, v54, v55
	v_add_f32_e32 v49, v179, v51
	v_mov_b32_e32 v51, v8
	v_mov_b32_e32 v232, v8
	s_nop 1
	v_permlane32_swap_b32_e32 v51, v232
	v_cndmask_b32_e64 v51, v51, v232, s[4:5]
	v_mov_b32_e32 v55, v6
	v_mov_b32_e32 v56, v4
	v_mov_b32_e32 v57, v7
	v_exp_f32_e32 v14, v14
	s_waitcnt lgkmcnt(0)
	v_cndmask_b32_e64 v54, 0, v51, s[4:5]
	v_add_f32_e32 v54, v12, v54
	v_add_f32_e32 v11, v11, v54
	v_add_f32_e32 v54, v177, v54
	v_add_f32_e32 v10, v10, v11
	v_exp_f32_e32 v80, v54
	v_mov_b32_e32 v54, v9
	v_add_f32_e32 v13, v13, v10
	v_add_f32_e32 v10, v175, v10
	v_pk_add_f32 v[54:55], v[54:55], v[56:57]
	v_exp_f32_e32 v138, v10
	v_add_f32_e32 v10, v174, v13
	v_pk_add_f32 v[54:55], v[54:55], v[54:55] op_sel:[0,1] op_sel_hi:[1,0]
	v_exp_f32_e32 v139, v10
	v_add_f32_e32 v10, v8, v51
	v_mov_b32_e32 v8, v54
	v_mov_b32_e32 v231, v54
	s_nop 1
	v_permlane32_swap_b32_e32 v8, v231
	v_cndmask_b32_e64 v8, v8, v231, s[4:5]
	v_add_f32_e32 v11, v176, v11
	v_exp_f32_e32 v81, v11
	v_mov_b32_e32 v13, v2
	v_mov_b32_e32 v11, v5
	s_waitcnt lgkmcnt(0)
	v_cndmask_b32_e64 v4, 0, v8, s[4:5]
	v_pk_add_f32 v[10:11], v[12:13], v[10:11]
	v_mov_b32_e32 v55, v0
	v_add_f32_e32 v4, v10, v4
	v_add_f32_e32 v7, v7, v4
	v_add_f32_e32 v4, v173, v4
	v_add_f32_e32 v6, v6, v7
	v_exp_f32_e32 v12, v4
	v_add_f32_e32 v4, v172, v7
	v_add_f32_e32 v9, v9, v6
	v_exp_f32_e32 v13, v4
	v_add_f32_e32 v4, v171, v6
	v_exp_f32_e32 v51, v4
	v_add_f32_e32 v4, v170, v9
	v_mov_b32_e32 v9, v1
	v_pk_add_f32 v[6:7], v[54:55], v[8:9]
	v_exp_f32_e32 v56, v4
	v_pk_add_f32 v[6:7], v[6:7], v[10:11]
	v_mov_b32_e32 v0, v7
	v_mov_b32_e32 v230, v7
	s_nop 1
	v_permlane32_swap_b32_e32 v0, v230
	v_cndmask_b32_e64 v0, v0, v230, s[4:5]
	v_cvt_pk_bf16_f32 v8, v59, v58
	v_cvt_pk_bf16_f32 v10, v71, v70
	v_cvt_pk_bf16_f32 v11, v69, v52
	v_exp_f32_e32 v15, v15
	s_waitcnt lgkmcnt(0)
	v_cndmask_b32_e64 v4, 0, v0, s[4:5]
	v_add_f32_e32 v4, v6, v4
	v_add_f32_e32 v5, v5, v4
	v_add_f32_e32 v4, v169, v4
	v_exp_f32_e32 v9, v4
	v_add_f32_e32 v4, v168, v5
	v_add_f32_e32 v2, v2, v5
	v_exp_f32_e32 v5, v4
	v_add_f32_e32 v1, v1, v2
	v_add_f32_e32 v2, v167, v2
	v_add_f32_e32 v1, v166, v1
	v_exp_f32_e32 v2, v2
	v_exp_f32_e32 v1, v1
	v_add_f32_e32 v0, v7, v0
	v_add_f32_e32 v164, v6, v0
	v_cvt_pk_bf16_f32 v5, v5, v9
	v_cvt_pk_bf16_f32 v9, v53, v48
	v_cvt_pk_bf16_f32 v6, v56, v51
	ds_read_b128 v[52:55], v224 offset:32512
	ds_read_b128 v[56:59], v224 offset:27968
	ds_read_b128 v[68:71], v224 offset:32576
	ds_read_b128 v[72:75], v224 offset:27904
	ds_read_b128 v[76:79], v224 offset:27936
	v_cvt_pk_bf16_f32 v4, v1, v2
	v_cvt_pk_bf16_f32 v7, v13, v12
	v_exp_f32_e32 v49, v49
	v_exp_f32_e32 v50, v50
	s_waitcnt lgkmcnt(1)
	v_mfma_f32_32x32x16_bf16 v[32:47], v[72:75], v[4:7], v[32:47]
	v_exp_f32_e32 v62, v62
	v_mfma_f32_32x32x16_bf16 v[16:31], v[52:55], v[4:7], v[16:31]
	v_cvt_pk_bf16_f32 v6, v50, v49
	v_cvt_pk_bf16_f32 v7, v15, v14
	ds_read_b128 v[12:15], v224 offset:32544
	ds_read_b128 v[48:51], v224 offset:28000
	ds_read_b128 v[52:55], v224 offset:32608
	v_cvt_pk_bf16_f32 v4, v139, v138
	v_cvt_pk_bf16_f32 v5, v81, v80
	v_mfma_f32_32x32x16_bf16 v[32:47], v[56:59], v[8:11], v[32:47]
	v_mfma_f32_32x32x16_bf16 v[16:31], v[68:71], v[8:11], v[16:31]
	v_cvt_pk_bf16_f32 v8, v67, v66
	v_cvt_pk_bf16_f32 v9, v65, v61
	v_cvt_pk_bf16_f32 v10, v64, v63
	v_cvt_pk_bf16_f32 v11, v62, v60
	s_waitcnt lgkmcnt(3)
	v_mfma_f32_32x32x16_bf16 v[32:47], v[76:79], v[4:7], v[32:47]
	s_waitcnt lgkmcnt(2)
	v_mfma_f32_32x32x16_bf16 v[16:31], v[12:15], v[4:7], v[16:31]
	s_waitcnt lgkmcnt(1)
	v_mfma_f32_32x32x16_bf16 v[32:47], v[48:51], v[8:11], v[32:47]
	s_waitcnt lgkmcnt(0)
	v_mfma_f32_32x32x16_bf16 v[16:31], v[52:55], v[8:11], v[16:31]
